# phase 7 sample-row down projection: all 33 fragment loads per wave hoisted, epilogue operand loads hoisted above the barrier
# speedup vs baseline: 1.0120x; 1.0036x over previous
.LBB0_1131:
	s_cmp_lt_i32 s92, 8
	s_cselect_b64 s[0:1], -1, 0
	s_cmp_gt_i32 s93, 7
	s_cselect_b64 s[2:3], -1, 0
	s_and_b64 s[0:1], s[0:1], s[2:3]
	s_andn2_b64 vcc, exec, s[0:1]
	s_cbranch_vccnz .LBB0_1251
	s_waitcnt vmcnt(0)
	v_mov_b32_e32 v5, v0
	s_lshl_b32 s2, s12, 4
	s_and_b32 s2, s2, 0x70
	v_and_b32_e32 v8, 15, v5
	v_or_b32_e32 v1, s2, v8
	v_readfirstlane_b32 s0, v5
	v_mul_u32_u24_e32 v2, 0xb00, v1
	s_ashr_i32 s1, s0, 6
	v_lshlrev_b32_e32 v2, 1, v2
	s_waitcnt lgkmcnt(0)
	v_mov_b32_e32 v3, 0
	v_lshl_add_u64 v[6:7], s[36:37], 0, v[2:3]
	s_mov_b64 s[2:3], 0x5800000
	s_mul_i32 s6, s1, 0x160
	v_lshl_add_u64 v[46:47], v[6:7], 0, s[2:3]
	s_lshl_b32 s2, s12, 2
	s_ashr_i32 s7, s6, 31
	s_andn2_b32 s2, s2, 31
	s_lshl_b64 s[8:9], s[6:7], 1
	s_add_u32 s8, s97, s8
	s_addc_u32 s9, s20, s9
	v_and_b32_e32 v2, 48, v5
	v_or_b32_e32 v8, s2, v8
	v_lshl_add_u64 v[6:7], s[8:9], 0, v[2:3]
	s_movk_i32 s3, 0x1600
	v_mad_i64_i32 v[48:49], s[8:9], v8, s3, v[6:7]
	v_or_b32_e32 v2, 16, v8
	v_bfe_u32 v4, v5, 4, 2
	v_mad_i64_i32 v[50:51], s[8:9], v2, s3, v[6:7]
	v_lshl_or_b32 v52, v4, 3, s6
	v_ashrrev_i32_e32 v53, 31, v52
	v_lshl_add_u64 v[54:55], v[52:53], 1, v[46:47]
	s_cmp_gt_i32 s1, 1
	s_cbranch_scc1 .Lpr7_noepi
	s_lshl_b32 s8, s1, 4
	s_add_i32 s8, s8, s2
	v_lshl_or_b32 v216, v4, 2, s8
	v_lshlrev_b32_e32 v218, 10, v1
	v_mov_b32_e32 v219, 0
	v_ashrrev_i32_e32 v217, 31, v216
	v_mul_u32_u24_e32 v220, 0x1800, v1
	v_lshl_add_u64 v[222:223], v[216:217], 0, v[218:219]
	v_lshlrev_b32_e32 v218, 2, v220
	v_lshl_add_u64 v[220:221], s[70:71], 0, v[218:219]
	v_lshl_add_u64 v[216:217], v[216:217], 2, v[220:221]
	s_mov_b32 s8, 0x35000
	v_add_co_u32_e32 v216, vcc, s8, v216
	v_lshlrev_b64 v[222:223], 2, v[222:223]
	s_nop 0
	v_addc_co_u32_e32 v217, vcc, 0, v217, vcc
	global_load_dwordx4 v[200:203], v[216:217], off
	v_lshl_add_u64 v[220:221], s[4:5], 0, v[222:223]
	global_load_dwordx4 v[204:207], v[220:221], off
.Lpr7_noepi:
	global_load_dwordx4 v[60:63], v[54:55], off
	global_load_dwordx4 v[64:67], v[48:49], off
	global_load_dwordx4 v[68:71], v[50:51], off
	global_load_dwordx4 v[72:75], v[54:55], off offset:64
	global_load_dwordx4 v[76:79], v[48:49], off offset:64
	global_load_dwordx4 v[80:83], v[50:51], off offset:64
	global_load_dwordx4 v[84:87], v[54:55], off offset:128
	global_load_dwordx4 v[88:91], v[48:49], off offset:128
	global_load_dwordx4 v[92:95], v[50:51], off offset:128
	global_load_dwordx4 v[96:99], v[54:55], off offset:192
	global_load_dwordx4 v[100:103], v[48:49], off offset:192
	global_load_dwordx4 v[104:107], v[50:51], off offset:192
	global_load_dwordx4 v[108:111], v[54:55], off offset:256
	global_load_dwordx4 v[112:115], v[48:49], off offset:256
	global_load_dwordx4 v[116:119], v[50:51], off offset:256
	global_load_dwordx4 v[120:123], v[54:55], off offset:320
	global_load_dwordx4 v[124:127], v[48:49], off offset:320
	global_load_dwordx4 v[128:131], v[50:51], off offset:320
	global_load_dwordx4 v[132:135], v[54:55], off offset:384
	global_load_dwordx4 v[136:139], v[48:49], off offset:384
	global_load_dwordx4 v[140:143], v[50:51], off offset:384
	global_load_dwordx4 v[144:147], v[54:55], off offset:448
	global_load_dwordx4 v[148:151], v[48:49], off offset:448
	global_load_dwordx4 v[152:155], v[50:51], off offset:448
	global_load_dwordx4 v[156:159], v[54:55], off offset:512
	global_load_dwordx4 v[160:163], v[48:49], off offset:512
	global_load_dwordx4 v[164:167], v[50:51], off offset:512
	global_load_dwordx4 v[168:171], v[54:55], off offset:576
	global_load_dwordx4 v[172:175], v[48:49], off offset:576
	global_load_dwordx4 v[176:179], v[50:51], off offset:576
	global_load_dwordx4 v[180:183], v[54:55], off offset:640
	global_load_dwordx4 v[184:187], v[48:49], off offset:640
	global_load_dwordx4 v[188:191], v[50:51], off offset:640
	s_lshl_b32 s3, s1, 11
	v_and_b32_e32 v5, 63, v5
	s_add_i32 s3, s3, 0
	v_lshl_add_u32 v2, v5, 4, s3
	s_cmp_gt_i32 s1, 1
	s_waitcnt vmcnt(30)
	v_mfma_f32_16x16x32_bf16 v[6:9], v[64:67], v[60:63], 0
	v_mfma_f32_16x16x32_bf16 v[10:13], v[68:71], v[60:63], 0
	s_waitcnt vmcnt(27)
	v_mfma_f32_16x16x32_bf16 v[6:9], v[76:79], v[72:75], v[6:9]
	v_mfma_f32_16x16x32_bf16 v[10:13], v[80:83], v[72:75], v[10:13]
	s_waitcnt vmcnt(24)
	v_mfma_f32_16x16x32_bf16 v[6:9], v[88:91], v[84:87], v[6:9]
	v_mfma_f32_16x16x32_bf16 v[10:13], v[92:95], v[84:87], v[10:13]
	s_waitcnt vmcnt(21)
	v_mfma_f32_16x16x32_bf16 v[6:9], v[100:103], v[96:99], v[6:9]
	v_mfma_f32_16x16x32_bf16 v[10:13], v[104:107], v[96:99], v[10:13]
	s_waitcnt vmcnt(18)
	v_mfma_f32_16x16x32_bf16 v[6:9], v[112:115], v[108:111], v[6:9]
	v_mfma_f32_16x16x32_bf16 v[10:13], v[116:119], v[108:111], v[10:13]
	s_waitcnt vmcnt(15)
	v_mfma_f32_16x16x32_bf16 v[6:9], v[124:127], v[120:123], v[6:9]
	v_mfma_f32_16x16x32_bf16 v[10:13], v[128:131], v[120:123], v[10:13]
	s_waitcnt vmcnt(12)
	v_mfma_f32_16x16x32_bf16 v[6:9], v[136:139], v[132:135], v[6:9]
	v_mfma_f32_16x16x32_bf16 v[10:13], v[140:143], v[132:135], v[10:13]
	s_waitcnt vmcnt(9)
	v_mfma_f32_16x16x32_bf16 v[6:9], v[148:151], v[144:147], v[6:9]
	v_mfma_f32_16x16x32_bf16 v[10:13], v[152:155], v[144:147], v[10:13]
	s_waitcnt vmcnt(6)
	v_mfma_f32_16x16x32_bf16 v[6:9], v[160:163], v[156:159], v[6:9]
	v_mfma_f32_16x16x32_bf16 v[10:13], v[164:167], v[156:159], v[10:13]
	s_waitcnt vmcnt(3)
	v_mfma_f32_16x16x32_bf16 v[6:9], v[172:175], v[168:171], v[6:9]
	v_mfma_f32_16x16x32_bf16 v[10:13], v[176:179], v[168:171], v[10:13]
	s_waitcnt vmcnt(0)
	v_mfma_f32_16x16x32_bf16 v[6:9], v[184:187], v[180:183], v[6:9]
	v_mfma_f32_16x16x32_bf16 v[10:13], v[188:191], v[180:183], v[10:13]
	s_nop 6
	ds_write_b128 v2, v[6:9]
	ds_write_b128 v2, v[10:13] offset:1024
	s_waitcnt lgkmcnt(0)
	s_barrier
	s_cbranch_scc1 .LBB0_1134
	s_lshl_b32 s1, s1, 4
	s_add_i32 s1, s1, s2
	v_lshl_or_b32 v6, v4, 2, s1
	v_lshlrev_b32_e32 v2, 10, v1
	v_ashrrev_i32_e32 v7, 31, v6
	v_mul_u32_u24_e32 v1, 0x1800, v1
	v_lshl_add_u64 v[10:11], v[6:7], 0, v[2:3]
	v_lshlrev_b32_e32 v2, 2, v1
	v_lshl_add_u64 v[8:9], s[70:71], 0, v[2:3]
	v_lshl_add_u64 v[6:7], v[6:7], 2, v[8:9]
	s_mov_b32 s1, 0x35000
	v_add_co_u32_e32 v6, vcc, s1, v6
	v_lshlrev_b64 v[46:47], 2, v[10:11]
	s_nop 0
	v_addc_co_u32_e32 v7, vcc, 0, v7, vcc
	v_mov_b32_e32 v6, v200
	v_mov_b32_e32 v7, v201
	v_mov_b32_e32 v8, v202
	v_mov_b32_e32 v9, v203
	v_lshl_add_u64 v[10:11], s[4:5], 0, v[46:47]
	v_mov_b32_e32 v10, v204
	v_mov_b32_e32 v11, v205
	v_mov_b32_e32 v12, v206
	v_mov_b32_e32 v13, v207
	s_and_b32 s1, s0, 0xfffffc0
	s_lshl_b32 s1, s1, 4
	s_add_i32 s1, s1, 0
	v_lshl_add_u32 v1, v5, 4, s1
	ds_read_b128 v[14:17], v1
	ds_read_b128 v[18:21], v1 offset:2048
	ds_read_b128 v[22:25], v1 offset:4096
	ds_read_b128 v[26:29], v1 offset:6144
	ds_read_b128 v[30:33], v1 offset:8192
	ds_read_b128 v[34:37], v1 offset:10240
	ds_read_b128 v[38:41], v1 offset:12288
	ds_read_b128 v[42:45], v1 offset:14336
	s_waitcnt lgkmcnt(6)
	v_pk_add_f32 v[4:5], v[16:17], v[20:21]
	v_pk_add_f32 v[14:15], v[14:15], v[18:19]
	s_waitcnt lgkmcnt(5)
	v_pk_add_f32 v[4:5], v[4:5], v[24:25]
	v_pk_add_f32 v[14:15], v[14:15], v[22:23]
	s_waitcnt lgkmcnt(4)
	v_pk_add_f32 v[4:5], v[4:5], v[28:29]
	v_pk_add_f32 v[14:15], v[14:15], v[26:27]
	s_waitcnt lgkmcnt(3)
	v_pk_add_f32 v[4:5], v[4:5], v[32:33]
	v_pk_add_f32 v[14:15], v[14:15], v[30:31]
	s_waitcnt lgkmcnt(2)
	v_pk_add_f32 v[4:5], v[4:5], v[36:37]
	v_pk_add_f32 v[14:15], v[14:15], v[34:35]
	s_waitcnt lgkmcnt(1)
	v_pk_add_f32 v[4:5], v[4:5], v[40:41]
	v_pk_add_f32 v[14:15], v[14:15], v[38:39]
	v_lshl_add_u64 v[46:47], s[68:69], 0, v[46:47]
	s_waitcnt lgkmcnt(0)
	v_pk_add_f32 v[4:5], v[4:5], v[44:45]
	v_pk_add_f32 v[14:15], v[14:15], v[42:43]
	s_mov_b32 s0, 0x3f9837f0
	v_add_co_u32_e32 v46, vcc, 0x14000000, v46
	s_waitcnt vmcnt(1)
	v_pk_add_f32 v[8:9], v[8:9], 1.0 op_sel_hi:[1,0]
	v_pk_add_f32 v[6:7], v[6:7], 1.0 op_sel_hi:[1,0]
	v_pk_mul_f32 v[4:5], v[4:5], v[8:9]
	v_pk_mul_f32 v[8:9], v[14:15], v[6:7]
	s_waitcnt vmcnt(0)
	v_pk_fma_f32 v[6:7], v[12:13], s[0:1], v[4:5] op_sel_hi:[1,0,1]
	v_pk_fma_f32 v[4:5], v[10:11], s[0:1], v[8:9] op_sel_hi:[1,0,1]
	v_addc_co_u32_e32 v47, vcc, 0, v47, vcc
	global_store_dwordx4 v[46:47], v[4:7], off
